# rmsnorm (XCD-local) in two passes of 4 tokens: the XCD's most recently written x rows (still in its L2) first
# speedup vs baseline: 1.0175x; 1.0042x over previous
.LBB0_69:
	s_andn2_b64 vcc, exec, s[0:1]
	s_cbranch_vccnz .LBB0_74
	v_and_b32_e32 v185, 63, v163
	v_lshlrev_b32_e32 v182, 4, v185
	v_lshlrev_b32_e32 v183, 3, v185
	v_xor_b32_e32 v184, 32, v185
	v_lshlrev_b32_e32 v184, 2, v184
	v_lshrrev_b32_e32 v186, 6, v163
	v_readlane_b32 s2, v236, 47
	v_readlane_b32 s3, v236, 48
	global_load_dword v185, v[164:165], off
	s_nop 3
	global_load_dwordx4 v[130:133], v182, s[2:3] offset:0
	global_load_dwordx4 v[134:137], v182, s[2:3] offset:1024
	global_load_dwordx4 v[138:141], v182, s[2:3] offset:2048
	global_load_dwordx4 v[142:145], v182, s[2:3] offset:3072
	v_readlane_b32 s2, v237, 0
	v_readfirstlane_b32 s3, v186
	s_and_b32 s4, s2, 7
	s_lshl_b32 s4, s4, 11
	s_lshr_b32 s2, s2, 3
	s_lshl_b32 s2, s2, 2
	s_add_i32 s2, s2, s3
	s_add_i32 s2, s2, s4
	s_add_i32 s2, s2, 0x400
	s_waitcnt vmcnt(4)
	s_movk_i32 s3, 0x100

.Lr8_ld3:
	s_waitcnt vmcnt(0)
	v_mul_f32_e32 v146, v2, v2
	v_fmac_f32_e32 v146, v3, v3
	v_fmac_f32_e32 v146, v4, v4
	v_fmac_f32_e32 v146, v5, v5
	v_fmac_f32_e32 v146, v6, v6
	v_fmac_f32_e32 v146, v7, v7
	v_fmac_f32_e32 v146, v8, v8
	v_fmac_f32_e32 v146, v9, v9
	v_fmac_f32_e32 v146, v10, v10
	v_fmac_f32_e32 v146, v11, v11
	v_fmac_f32_e32 v146, v12, v12
	v_fmac_f32_e32 v146, v13, v13
	v_fmac_f32_e32 v146, v14, v14
	v_fmac_f32_e32 v146, v15, v15
	v_fmac_f32_e32 v146, v16, v16
	v_fmac_f32_e32 v146, v17, v17
	v_mul_f32_e32 v147, v18, v18
	v_fmac_f32_e32 v147, v19, v19
	v_fmac_f32_e32 v147, v20, v20
	v_fmac_f32_e32 v147, v21, v21
	v_fmac_f32_e32 v147, v22, v22
	v_fmac_f32_e32 v147, v23, v23
	v_fmac_f32_e32 v147, v24, v24
	v_fmac_f32_e32 v147, v25, v25
	v_fmac_f32_e32 v147, v26, v26
	v_fmac_f32_e32 v147, v27, v27
	v_fmac_f32_e32 v147, v28, v28
	v_fmac_f32_e32 v147, v29, v29
	v_fmac_f32_e32 v147, v30, v30
	v_fmac_f32_e32 v147, v31, v31
	v_fmac_f32_e32 v147, v32, v32
	v_fmac_f32_e32 v147, v33, v33
	v_mul_f32_e32 v148, v34, v34
	v_fmac_f32_e32 v148, v35, v35
	v_fmac_f32_e32 v148, v36, v36
	v_fmac_f32_e32 v148, v37, v37
	v_fmac_f32_e32 v148, v38, v38
	v_fmac_f32_e32 v148, v39, v39
	v_fmac_f32_e32 v148, v40, v40
	v_fmac_f32_e32 v148, v41, v41
	v_fmac_f32_e32 v148, v42, v42
	v_fmac_f32_e32 v148, v43, v43
	v_fmac_f32_e32 v148, v44, v44
	v_fmac_f32_e32 v148, v45, v45
	v_fmac_f32_e32 v148, v46, v46
	v_fmac_f32_e32 v148, v47, v47
	v_fmac_f32_e32 v148, v48, v48
	v_fmac_f32_e32 v148, v49, v49
	v_mul_f32_e32 v149, v50, v50
	v_fmac_f32_e32 v149, v51, v51
	v_fmac_f32_e32 v149, v52, v52
	v_fmac_f32_e32 v149, v53, v53
	v_fmac_f32_e32 v149, v54, v54
	v_fmac_f32_e32 v149, v55, v55
	v_fmac_f32_e32 v149, v56, v56
	v_fmac_f32_e32 v149, v57, v57
	v_fmac_f32_e32 v149, v58, v58
	v_fmac_f32_e32 v149, v59, v59
	v_fmac_f32_e32 v149, v60, v60
	v_fmac_f32_e32 v149, v61, v61
	v_fmac_f32_e32 v149, v62, v62
	v_fmac_f32_e32 v149, v63, v63
	v_fmac_f32_e32 v149, v64, v64
	v_fmac_f32_e32 v149, v65, v65
	ds_swizzle_b32 v154, v146 offset:0x41f
	ds_swizzle_b32 v155, v147 offset:0x41f
	ds_swizzle_b32 v156, v148 offset:0x41f
	ds_swizzle_b32 v157, v149 offset:0x41f
	s_waitcnt lgkmcnt(0)
	v_add_f32_e32 v146, v146, v154
	v_add_f32_e32 v147, v147, v155
	v_add_f32_e32 v148, v148, v156
	v_add_f32_e32 v149, v149, v157
	s_nop 0
	ds_swizzle_b32 v154, v146 offset:0x81f
	ds_swizzle_b32 v155, v147 offset:0x81f
	ds_swizzle_b32 v156, v148 offset:0x81f
	ds_swizzle_b32 v157, v149 offset:0x81f
	s_waitcnt lgkmcnt(0)
	v_add_f32_e32 v146, v146, v154
	v_add_f32_e32 v147, v147, v155
	v_add_f32_e32 v148, v148, v156
	v_add_f32_e32 v149, v149, v157
	s_nop 0
	ds_swizzle_b32 v154, v146 offset:0x101f
	ds_swizzle_b32 v155, v147 offset:0x101f
	ds_swizzle_b32 v156, v148 offset:0x101f
	ds_swizzle_b32 v157, v149 offset:0x101f
	s_waitcnt lgkmcnt(0)
	v_add_f32_e32 v146, v146, v154
	v_add_f32_e32 v147, v147, v155
	v_add_f32_e32 v148, v148, v156
	v_add_f32_e32 v149, v149, v157
	s_nop 0
	ds_swizzle_b32 v154, v146 offset:0x201f
	ds_swizzle_b32 v155, v147 offset:0x201f
	ds_swizzle_b32 v156, v148 offset:0x201f
	ds_swizzle_b32 v157, v149 offset:0x201f
	s_waitcnt lgkmcnt(0)
	v_add_f32_e32 v146, v146, v154
	v_add_f32_e32 v147, v147, v155
	v_add_f32_e32 v148, v148, v156
	v_add_f32_e32 v149, v149, v157
	s_nop 0
	ds_swizzle_b32 v154, v146 offset:0x401f
	ds_swizzle_b32 v155, v147 offset:0x401f
	ds_swizzle_b32 v156, v148 offset:0x401f
	ds_swizzle_b32 v157, v149 offset:0x401f
	s_waitcnt lgkmcnt(0)
	v_add_f32_e32 v146, v146, v154
	v_add_f32_e32 v147, v147, v155
	v_add_f32_e32 v148, v148, v156
	v_add_f32_e32 v149, v149, v157
	s_nop 0
	ds_bpermute_b32 v154, v184, v146
	ds_bpermute_b32 v155, v184, v147
	ds_bpermute_b32 v156, v184, v148
	ds_bpermute_b32 v157, v184, v149
	s_waitcnt lgkmcnt(0)
	v_add_f32_e32 v146, v146, v154
	v_add_f32_e32 v147, v147, v155
	v_add_f32_e32 v148, v148, v156
	v_add_f32_e32 v149, v149, v157
	v_fmamk_f32 v146, v146, 0x3a800000, v167
	v_fmamk_f32 v147, v147, 0x3a800000, v167
	v_fmamk_f32 v148, v148, 0x3a800000, v167
	v_fmamk_f32 v149, v149, 0x3a800000, v167
	v_rsq_f32_e32 v146, v146
	v_rsq_f32_e32 v147, v147
	v_rsq_f32_e32 v148, v148
	v_rsq_f32_e32 v149, v149
	s_nop 0
	s_mov_b32 s6, s2
	s_mul_i32 s4, s2, 0x880
	s_add_u32 s4, s80, s4
	s_addc_u32 s5, s81, 0
	s_cmpk_ge_u32 s6, 0x4000
	s_cbranch_scc1 .Lr8_stp0
	v_mul_f32_e32 v154, v2, v146
	v_mul_f32_e32 v155, v3, v146
	v_mul_f32_e32 v156, v4, v146
	v_mul_f32_e32 v157, v5, v146
	v_mul_f32_e32 v154, v130, v154
	v_mul_f32_e32 v155, v131, v155
	v_mul_f32_e32 v156, v132, v156
	v_mul_f32_e32 v157, v133, v157
	v_cvt_pk_bf16_f32 v188, v154, v155
	v_cvt_pk_bf16_f32 v189, v156, v157
	global_store_dwordx2 v183, v[188:189], s[4:5] offset:0
	s_nop 0
	v_mul_f32_e32 v154, v6, v146
	v_mul_f32_e32 v155, v7, v146
	v_mul_f32_e32 v156, v8, v146
	v_mul_f32_e32 v157, v9, v146
	v_mul_f32_e32 v154, v134, v154
	v_mul_f32_e32 v155, v135, v155
	v_mul_f32_e32 v156, v136, v156
	v_mul_f32_e32 v157, v137, v157
	v_cvt_pk_bf16_f32 v188, v154, v155
	v_cvt_pk_bf16_f32 v189, v156, v157
	global_store_dwordx2 v183, v[188:189], s[4:5] offset:512
	s_nop 0
	v_mul_f32_e32 v154, v10, v146
	v_mul_f32_e32 v155, v11, v146
	v_mul_f32_e32 v156, v12, v146
	v_mul_f32_e32 v157, v13, v146
	v_mul_f32_e32 v154, v138, v154
	v_mul_f32_e32 v155, v139, v155
	v_mul_f32_e32 v156, v140, v156
	v_mul_f32_e32 v157, v141, v157
	v_cvt_pk_bf16_f32 v188, v154, v155
	v_cvt_pk_bf16_f32 v189, v156, v157
	global_store_dwordx2 v183, v[188:189], s[4:5] offset:1024
	s_nop 0
	v_mul_f32_e32 v154, v14, v146
	v_mul_f32_e32 v155, v15, v146
	v_mul_f32_e32 v156, v16, v146
	v_mul_f32_e32 v157, v17, v146
	v_mul_f32_e32 v154, v142, v154
	v_mul_f32_e32 v155, v143, v155
	v_mul_f32_e32 v156, v144, v156
	v_mul_f32_e32 v157, v145, v157
	v_cvt_pk_bf16_f32 v188, v154, v155
	v_cvt_pk_bf16_f32 v189, v156, v157
	global_store_dwordx2 v183, v[188:189], s[4:5] offset:1536
	s_nop 0

.Lr8_stp3:
.Lr8_next:
	s_bitcmp1_b32 s2, 10
	s_cbranch_scc0 .Lr8_end
	s_sub_u32 s2, s2, 0x400
	s_branch .Lr8_outer

.LBB0_523:
	s_or_b64 exec, exec, s[2:3]
	v_and_b32_e32 v185, 63, v163
	v_lshlrev_b32_e32 v182, 4, v185
	v_lshlrev_b32_e32 v183, 3, v185
	v_xor_b32_e32 v184, 32, v185
	v_lshlrev_b32_e32 v184, 2, v184
	v_lshrrev_b32_e32 v186, 6, v163
	v_readlane_b32 s2, v235, 26
	v_readlane_b32 s3, v235, 27
	global_load_dword v185, v[164:165], off
	s_nop 3
	global_load_dwordx4 v[130:133], v182, s[2:3] offset:0
	global_load_dwordx4 v[134:137], v182, s[2:3] offset:1024
	global_load_dwordx4 v[138:141], v182, s[2:3] offset:2048
	global_load_dwordx4 v[142:145], v182, s[2:3] offset:3072
	v_readlane_b32 s2, v237, 0
	v_readfirstlane_b32 s3, v186
	s_and_b32 s4, s2, 7
	s_lshl_b32 s4, s4, 11
	s_lshr_b32 s2, s2, 3
	s_lshl_b32 s2, s2, 2
	s_add_i32 s2, s2, s3
	s_add_i32 s2, s2, s4
	s_add_i32 s2, s2, 0x400
	s_waitcnt vmcnt(4)
	s_movk_i32 s3, 0x100

.Lr0_ld3:
	s_waitcnt vmcnt(0)
	v_mul_f32_e32 v146, v2, v2
	v_fmac_f32_e32 v146, v3, v3
	v_fmac_f32_e32 v146, v4, v4
	v_fmac_f32_e32 v146, v5, v5
	v_fmac_f32_e32 v146, v6, v6
	v_fmac_f32_e32 v146, v7, v7
	v_fmac_f32_e32 v146, v8, v8
	v_fmac_f32_e32 v146, v9, v9
	v_fmac_f32_e32 v146, v10, v10
	v_fmac_f32_e32 v146, v11, v11
	v_fmac_f32_e32 v146, v12, v12
	v_fmac_f32_e32 v146, v13, v13
	v_fmac_f32_e32 v146, v14, v14
	v_fmac_f32_e32 v146, v15, v15
	v_fmac_f32_e32 v146, v16, v16
	v_fmac_f32_e32 v146, v17, v17
	v_mul_f32_e32 v147, v18, v18
	v_fmac_f32_e32 v147, v19, v19
	v_fmac_f32_e32 v147, v20, v20
	v_fmac_f32_e32 v147, v21, v21
	v_fmac_f32_e32 v147, v22, v22
	v_fmac_f32_e32 v147, v23, v23
	v_fmac_f32_e32 v147, v24, v24
	v_fmac_f32_e32 v147, v25, v25
	v_fmac_f32_e32 v147, v26, v26
	v_fmac_f32_e32 v147, v27, v27
	v_fmac_f32_e32 v147, v28, v28
	v_fmac_f32_e32 v147, v29, v29
	v_fmac_f32_e32 v147, v30, v30
	v_fmac_f32_e32 v147, v31, v31
	v_fmac_f32_e32 v147, v32, v32
	v_fmac_f32_e32 v147, v33, v33
	v_mul_f32_e32 v148, v34, v34
	v_fmac_f32_e32 v148, v35, v35
	v_fmac_f32_e32 v148, v36, v36
	v_fmac_f32_e32 v148, v37, v37
	v_fmac_f32_e32 v148, v38, v38
	v_fmac_f32_e32 v148, v39, v39
	v_fmac_f32_e32 v148, v40, v40
	v_fmac_f32_e32 v148, v41, v41
	v_fmac_f32_e32 v148, v42, v42
	v_fmac_f32_e32 v148, v43, v43
	v_fmac_f32_e32 v148, v44, v44
	v_fmac_f32_e32 v148, v45, v45
	v_fmac_f32_e32 v148, v46, v46
	v_fmac_f32_e32 v148, v47, v47
	v_fmac_f32_e32 v148, v48, v48
	v_fmac_f32_e32 v148, v49, v49
	v_mul_f32_e32 v149, v50, v50
	v_fmac_f32_e32 v149, v51, v51
	v_fmac_f32_e32 v149, v52, v52
	v_fmac_f32_e32 v149, v53, v53
	v_fmac_f32_e32 v149, v54, v54
	v_fmac_f32_e32 v149, v55, v55
	v_fmac_f32_e32 v149, v56, v56
	v_fmac_f32_e32 v149, v57, v57
	v_fmac_f32_e32 v149, v58, v58
	v_fmac_f32_e32 v149, v59, v59
	v_fmac_f32_e32 v149, v60, v60
	v_fmac_f32_e32 v149, v61, v61
	v_fmac_f32_e32 v149, v62, v62
	v_fmac_f32_e32 v149, v63, v63
	v_fmac_f32_e32 v149, v64, v64
	v_fmac_f32_e32 v149, v65, v65
	ds_swizzle_b32 v154, v146 offset:0x41f
	ds_swizzle_b32 v155, v147 offset:0x41f
	ds_swizzle_b32 v156, v148 offset:0x41f
	ds_swizzle_b32 v157, v149 offset:0x41f
	s_waitcnt lgkmcnt(0)
	v_add_f32_e32 v146, v146, v154
	v_add_f32_e32 v147, v147, v155
	v_add_f32_e32 v148, v148, v156
	v_add_f32_e32 v149, v149, v157
	s_nop 0
	ds_swizzle_b32 v154, v146 offset:0x81f
	ds_swizzle_b32 v155, v147 offset:0x81f
	ds_swizzle_b32 v156, v148 offset:0x81f
	ds_swizzle_b32 v157, v149 offset:0x81f
	s_waitcnt lgkmcnt(0)
	v_add_f32_e32 v146, v146, v154
	v_add_f32_e32 v147, v147, v155
	v_add_f32_e32 v148, v148, v156
	v_add_f32_e32 v149, v149, v157
	s_nop 0
	ds_swizzle_b32 v154, v146 offset:0x101f
	ds_swizzle_b32 v155, v147 offset:0x101f
	ds_swizzle_b32 v156, v148 offset:0x101f
	ds_swizzle_b32 v157, v149 offset:0x101f
	s_waitcnt lgkmcnt(0)
	v_add_f32_e32 v146, v146, v154
	v_add_f32_e32 v147, v147, v155
	v_add_f32_e32 v148, v148, v156
	v_add_f32_e32 v149, v149, v157
	s_nop 0
	ds_swizzle_b32 v154, v146 offset:0x201f
	ds_swizzle_b32 v155, v147 offset:0x201f
	ds_swizzle_b32 v156, v148 offset:0x201f
	ds_swizzle_b32 v157, v149 offset:0x201f
	s_waitcnt lgkmcnt(0)
	v_add_f32_e32 v146, v146, v154
	v_add_f32_e32 v147, v147, v155
	v_add_f32_e32 v148, v148, v156
	v_add_f32_e32 v149, v149, v157
	s_nop 0
	ds_swizzle_b32 v154, v146 offset:0x401f
	ds_swizzle_b32 v155, v147 offset:0x401f
	ds_swizzle_b32 v156, v148 offset:0x401f
	ds_swizzle_b32 v157, v149 offset:0x401f
	s_waitcnt lgkmcnt(0)
	v_add_f32_e32 v146, v146, v154
	v_add_f32_e32 v147, v147, v155
	v_add_f32_e32 v148, v148, v156
	v_add_f32_e32 v149, v149, v157
	s_nop 0
	ds_bpermute_b32 v154, v184, v146
	ds_bpermute_b32 v155, v184, v147
	ds_bpermute_b32 v156, v184, v148
	ds_bpermute_b32 v157, v184, v149
	s_waitcnt lgkmcnt(0)
	v_add_f32_e32 v146, v146, v154
	v_add_f32_e32 v147, v147, v155
	v_add_f32_e32 v148, v148, v156
	v_add_f32_e32 v149, v149, v157
	v_fmamk_f32 v146, v146, 0x3a800000, v167
	v_fmamk_f32 v147, v147, 0x3a800000, v167
	v_fmamk_f32 v148, v148, 0x3a800000, v167
	v_fmamk_f32 v149, v149, 0x3a800000, v167
	v_rsq_f32_e32 v146, v146
	v_rsq_f32_e32 v147, v147
	v_rsq_f32_e32 v148, v148
	v_rsq_f32_e32 v149, v149
	s_nop 0
	v_readlane_b32 s0, v235, 28
	v_readlane_b32 s1, v235, 29
	s_cmp_eq_u64 s[0:1], 0
	s_cbranch_scc1 .Lr0_plain
	s_mov_b32 s6, s2
	s_mul_i32 s4, s2, 0x880
	s_add_u32 s4, s80, s4
	s_addc_u32 s5, s81, 0
	s_lshl_b32 s7, s2, 12
	s_add_u32 s0, s0, s7
	s_addc_u32 s1, s1, 0
	s_cmpk_ge_u32 s6, 0x4000
	s_cbranch_scc1 .Lr0_stx0
	global_store_dwordx4 v182, v[2:5], s[0:1] offset:0
	global_store_dwordx4 v182, v[6:9], s[0:1] offset:1024
	global_store_dwordx4 v182, v[10:13], s[0:1] offset:2048
	global_store_dwordx4 v182, v[14:17], s[0:1] offset:3072
	v_mul_f32_e32 v154, v2, v146
	v_mul_f32_e32 v155, v3, v146
	v_mul_f32_e32 v156, v4, v146
	v_mul_f32_e32 v157, v5, v146
	v_mul_f32_e32 v154, v130, v154
	v_mul_f32_e32 v155, v131, v155
	v_mul_f32_e32 v156, v132, v156
	v_mul_f32_e32 v157, v133, v157
	v_cvt_pk_bf16_f32 v188, v154, v155
	v_cvt_pk_bf16_f32 v189, v156, v157
	global_store_dwordx2 v183, v[188:189], s[4:5] offset:0
	s_nop 0
	v_mul_f32_e32 v154, v6, v146
	v_mul_f32_e32 v155, v7, v146
	v_mul_f32_e32 v156, v8, v146
	v_mul_f32_e32 v157, v9, v146
	v_mul_f32_e32 v154, v134, v154
	v_mul_f32_e32 v155, v135, v155
	v_mul_f32_e32 v156, v136, v156
	v_mul_f32_e32 v157, v137, v157
	v_cvt_pk_bf16_f32 v188, v154, v155
	v_cvt_pk_bf16_f32 v189, v156, v157
	global_store_dwordx2 v183, v[188:189], s[4:5] offset:512
	s_nop 0
	v_mul_f32_e32 v154, v10, v146
	v_mul_f32_e32 v155, v11, v146
	v_mul_f32_e32 v156, v12, v146
	v_mul_f32_e32 v157, v13, v146
	v_mul_f32_e32 v154, v138, v154
	v_mul_f32_e32 v155, v139, v155
	v_mul_f32_e32 v156, v140, v156
	v_mul_f32_e32 v157, v141, v157
	v_cvt_pk_bf16_f32 v188, v154, v155
	v_cvt_pk_bf16_f32 v189, v156, v157
	global_store_dwordx2 v183, v[188:189], s[4:5] offset:1024
	s_nop 0
	v_mul_f32_e32 v154, v14, v146
	v_mul_f32_e32 v155, v15, v146
	v_mul_f32_e32 v156, v16, v146
	v_mul_f32_e32 v157, v17, v146
	v_mul_f32_e32 v154, v142, v154
	v_mul_f32_e32 v155, v143, v155
	v_mul_f32_e32 v156, v144, v156
	v_mul_f32_e32 v157, v145, v157
	v_cvt_pk_bf16_f32 v188, v154, v155
	v_cvt_pk_bf16_f32 v189, v156, v157
	global_store_dwordx2 v183, v[188:189], s[4:5] offset:1536
	s_nop 0

.Lr0_stx2:
	s_mul_i32 s7, s3, 0x880
	s_add_u32 s4, s4, s7
	s_addc_u32 s5, s5, 0
	s_lshl_b32 s7, s3, 12
	s_add_u32 s0, s0, s7
	s_addc_u32 s1, s1, 0
	s_add_i32 s6, s6, s3
	s_cmpk_ge_u32 s6, 0x4000
	s_cbranch_scc1 .Lr0_stx3
	global_store_dwordx4 v182, v[50:53], s[0:1] offset:0
	global_store_dwordx4 v182, v[54:57], s[0:1] offset:1024
	global_store_dwordx4 v182, v[58:61], s[0:1] offset:2048
	global_store_dwordx4 v182, v[62:65], s[0:1] offset:3072
	v_mul_f32_e32 v154, v50, v149
	v_mul_f32_e32 v155, v51, v149
	v_mul_f32_e32 v156, v52, v149
	v_mul_f32_e32 v157, v53, v149
	v_mul_f32_e32 v154, v130, v154
	v_mul_f32_e32 v155, v131, v155
	v_mul_f32_e32 v156, v132, v156
	v_mul_f32_e32 v157, v133, v157
	v_cvt_pk_bf16_f32 v188, v154, v155
	v_cvt_pk_bf16_f32 v189, v156, v157
	global_store_dwordx2 v183, v[188:189], s[4:5] offset:0
	s_nop 0
	v_mul_f32_e32 v154, v54, v149
	v_mul_f32_e32 v155, v55, v149
	v_mul_f32_e32 v156, v56, v149
	v_mul_f32_e32 v157, v57, v149
	v_mul_f32_e32 v154, v134, v154
	v_mul_f32_e32 v155, v135, v155
	v_mul_f32_e32 v156, v136, v156
	v_mul_f32_e32 v157, v137, v157
	v_cvt_pk_bf16_f32 v188, v154, v155
	v_cvt_pk_bf16_f32 v189, v156, v157
	global_store_dwordx2 v183, v[188:189], s[4:5] offset:512
	s_nop 0
	v_mul_f32_e32 v154, v58, v149
	v_mul_f32_e32 v155, v59, v149
	v_mul_f32_e32 v156, v60, v149
	v_mul_f32_e32 v157, v61, v149
	v_mul_f32_e32 v154, v138, v154
	v_mul_f32_e32 v155, v139, v155
	v_mul_f32_e32 v156, v140, v156
	v_mul_f32_e32 v157, v141, v157
	v_cvt_pk_bf16_f32 v188, v154, v155
	v_cvt_pk_bf16_f32 v189, v156, v157
	global_store_dwordx2 v183, v[188:189], s[4:5] offset:1024
	s_nop 0
	v_mul_f32_e32 v154, v62, v149
	v_mul_f32_e32 v155, v63, v149
	v_mul_f32_e32 v156, v64, v149
	v_mul_f32_e32 v157, v65, v149
	v_mul_f32_e32 v154, v142, v154
	v_mul_f32_e32 v155, v143, v155
	v_mul_f32_e32 v156, v144, v156
	v_mul_f32_e32 v157, v145, v157
	v_cvt_pk_bf16_f32 v188, v154, v155
	v_cvt_pk_bf16_f32 v189, v156, v157
	global_store_dwordx2 v183, v[188:189], s[4:5] offset:1536
	s_nop 0
.Lr0_stx3:
	s_branch .Lr0_next
